# step-4 epilogues of the delta-rule chunk prep (kk/qk masked decay) rewritten branch-free: batched LDS reads + cndmask instead of 16 exec-masked serial blocks
# speedup vs baseline: 1.0090x; 1.0090x over previous
.LBB0_137:
	v_lshl_or_b32 v21, s6, 5, v94
	v_lshl_or_b32 v22, s52, 5, v25
	v_lshl_add_u32 v18, v21, 2, 0
	v_lshl_add_u32 v19, v22, 2, 0
	v_add_u32_e32 v18, 0x24900, v18
	v_add_u32_e32 v19, 0x24900, v19
	ds_read_b32 v20, v18
	ds_read_b128 v[106:109], v19
	ds_read_b128 v[110:113], v19 offset:32
	ds_read_b128 v[114:117], v19 offset:64
	ds_read_b128 v[118:121], v19 offset:96
	v_sub_u32_e32 v21, v21, v22
	v_add_u32_e32 v21, 1, v21
	s_lshl_b32 s6, s6, 12
	s_lshl_b32 s7, s52, 11
	s_or_b32 s6, s6, s7
	v_lshl_or_b32 v22, v93, 4, s6
	s_add_i32 s6, s51, 0x8000
	v_add_u32_e32 v18, s6, v22
	s_add_i32 s6, s51, 0x8400
	v_add_u32_e32 v22, s6, v22
	s_waitcnt lgkmcnt(0)
	v_sub_f32_e32 v106, v20, v106
	v_sub_f32_e32 v107, v20, v107
	v_sub_f32_e32 v108, v20, v108
	v_sub_f32_e32 v109, v20, v109
	v_sub_f32_e32 v110, v20, v110
	v_sub_f32_e32 v111, v20, v111
	v_sub_f32_e32 v112, v20, v112
	v_sub_f32_e32 v113, v20, v113
	v_sub_f32_e32 v114, v20, v114
	v_sub_f32_e32 v115, v20, v115
	v_sub_f32_e32 v116, v20, v116
	v_sub_f32_e32 v117, v20, v117
	v_sub_f32_e32 v118, v20, v118
	v_sub_f32_e32 v119, v20, v119
	v_sub_f32_e32 v120, v20, v120
	v_sub_f32_e32 v121, v20, v121
	v_mul_f32_e32 v106, 0x3fb8aa3b, v106
	v_mul_f32_e32 v107, 0x3fb8aa3b, v107
	v_mul_f32_e32 v108, 0x3fb8aa3b, v108
	v_mul_f32_e32 v109, 0x3fb8aa3b, v109
	v_mul_f32_e32 v110, 0x3fb8aa3b, v110
	v_mul_f32_e32 v111, 0x3fb8aa3b, v111
	v_mul_f32_e32 v112, 0x3fb8aa3b, v112
	v_mul_f32_e32 v113, 0x3fb8aa3b, v113
	v_mul_f32_e32 v114, 0x3fb8aa3b, v114
	v_mul_f32_e32 v115, 0x3fb8aa3b, v115
	v_mul_f32_e32 v116, 0x3fb8aa3b, v116
	v_mul_f32_e32 v117, 0x3fb8aa3b, v117
	v_mul_f32_e32 v118, 0x3fb8aa3b, v118
	v_mul_f32_e32 v119, 0x3fb8aa3b, v119
	v_mul_f32_e32 v120, 0x3fb8aa3b, v120
	v_mul_f32_e32 v121, 0x3fb8aa3b, v121
	v_exp_f32_e32 v106, v106
	v_exp_f32_e32 v107, v107
	v_exp_f32_e32 v108, v108
	v_exp_f32_e32 v109, v109
	v_exp_f32_e32 v110, v110
	v_exp_f32_e32 v111, v111
	v_exp_f32_e32 v112, v112
	v_exp_f32_e32 v113, v113
	v_exp_f32_e32 v114, v114
	v_exp_f32_e32 v115, v115
	v_exp_f32_e32 v116, v116
	v_exp_f32_e32 v117, v117
	v_exp_f32_e32 v118, v118
	v_exp_f32_e32 v119, v119
	v_exp_f32_e32 v120, v120
	v_exp_f32_e32 v121, v121
	v_mul_f32_e32 v106, v2, v106
	v_mul_f32_e32 v107, v3, v107
	v_mul_f32_e32 v108, v4, v108
	v_mul_f32_e32 v109, v5, v109
	v_mul_f32_e32 v110, v6, v110
	v_mul_f32_e32 v111, v7, v111
	v_mul_f32_e32 v112, v8, v112
	v_mul_f32_e32 v113, v9, v113
	v_mul_f32_e32 v114, v10, v114
	v_mul_f32_e32 v115, v11, v115
	v_mul_f32_e32 v116, v12, v116
	v_mul_f32_e32 v117, v13, v117
	v_mul_f32_e32 v118, v14, v118
	v_mul_f32_e32 v119, v15, v119
	v_mul_f32_e32 v120, v16, v120
	v_mul_f32_e32 v121, v17, v121
	v_cmp_lt_i32_e32 vcc, 0, v21
	v_cmp_lt_i32_e64 s[28:29], 1, v21
	v_cmp_lt_i32_e64 s[6:7], 2, v21
	v_cndmask_b32_e32 v106, 0, v106, vcc
	v_cmp_lt_i32_e32 vcc, 3, v21
	v_cndmask_b32_e64 v107, 0, v107, s[28:29]
	v_cmp_lt_i32_e64 s[28:29], 8, v21
	v_cndmask_b32_e64 v108, 0, v108, s[6:7]
	v_cmp_lt_i32_e64 s[6:7], 9, v21
	v_cndmask_b32_e32 v109, 0, v109, vcc
	v_cmp_lt_i32_e32 vcc, 10, v21
	v_cndmask_b32_e64 v110, 0, v110, s[28:29]
	v_cmp_lt_i32_e64 s[28:29], 11, v21
	v_cndmask_b32_e64 v111, 0, v111, s[6:7]
	v_cmp_lt_i32_e64 s[6:7], 16, v21
	v_cndmask_b32_e32 v112, 0, v112, vcc
	v_cmp_lt_i32_e32 vcc, 17, v21
	v_cndmask_b32_e64 v113, 0, v113, s[28:29]
	v_cmp_lt_i32_e64 s[28:29], 18, v21
	v_cndmask_b32_e64 v114, 0, v114, s[6:7]
	v_cmp_lt_i32_e64 s[6:7], 19, v21
	v_cndmask_b32_e32 v115, 0, v115, vcc
	v_cmp_lt_i32_e32 vcc, 24, v21
	v_cndmask_b32_e64 v116, 0, v116, s[28:29]
	v_cmp_lt_i32_e64 s[28:29], 25, v21
	v_cndmask_b32_e64 v117, 0, v117, s[6:7]
	v_cmp_lt_i32_e64 s[6:7], 26, v21
	v_cndmask_b32_e32 v118, 0, v118, vcc
	v_cmp_lt_i32_e32 vcc, 27, v21
	v_cndmask_b32_e64 v119, 0, v119, s[28:29]
	v_cndmask_b32_e64 v120, 0, v120, s[6:7]
	v_cndmask_b32_e32 v121, 0, v121, vcc
	v_cvt_pk_bf16_f32 v122, v106, v107
	v_cvt_pk_bf16_f32 v123, v108, v109
	v_cvt_pk_bf16_f32 v124, v110, v111
	v_cvt_pk_bf16_f32 v125, v112, v113
	v_cvt_pk_bf16_f32 v126, v114, v115
	v_cvt_pk_bf16_f32 v127, v116, v117
	v_cvt_pk_bf16_f32 v128, v118, v119
	v_cvt_pk_bf16_f32 v129, v120, v121
	buffer_store_dwordx4 v[122:125], v18, s[72:75], 0 offen sc1
	buffer_store_dwordx4 v[126:129], v22, s[72:75], 0 offen sc1
	v_lshl_or_b32 v96, s52, 5, v94
	s_branch .LBB0_203
.LBB0_170:
	v_lshl_add_u32 v18, v96, 2, 0
	v_lshl_or_b32 v23, s53, 5, v25
	v_add_u32_e32 v18, 0x24900, v18
	v_lshl_add_u32 v20, v23, 2, 0
	ds_read_b32 v22, v18
	v_add_u32_e32 v19, 0x24900, v20
	v_add_u32_e32 v20, 0x24a00, v20
	ds_read_b128 v[106:109], v19
	ds_read_b128 v[110:113], v19 offset:32
	ds_read_b128 v[114:117], v19 offset:64
	ds_read_b128 v[118:121], v19 offset:96
	ds_read_b128 v[122:125], v20
	ds_read_b128 v[126:129], v20 offset:32
	ds_read_b128 v[26:29], v20 offset:64
	ds_read_b128 v[30:33], v20 offset:96
	v_readlane_b32 s6, v253, 51
	v_sub_u32_e32 v21, v23, v96
	v_add_u32_e32 v21, 27, v21
	v_lshlrev_b32_e32 v18, 8, v96
	v_lshlrev_b32_e32 v19, 2, v23
	v_add3_u32 v24, s6, v18, v19
	s_waitcnt lgkmcnt(0)
	v_sub_f32_e32 v106, v106, v22
	v_sub_f32_e32 v107, v107, v22
	v_sub_f32_e32 v108, v108, v22
	v_sub_f32_e32 v109, v109, v22
	v_sub_f32_e32 v110, v110, v22
	v_sub_f32_e32 v111, v111, v22
	v_sub_f32_e32 v112, v112, v22
	v_sub_f32_e32 v113, v113, v22
	v_sub_f32_e32 v114, v114, v22
	v_sub_f32_e32 v115, v115, v22
	v_sub_f32_e32 v116, v116, v22
	v_sub_f32_e32 v117, v117, v22
	v_sub_f32_e32 v118, v118, v22
	v_sub_f32_e32 v119, v119, v22
	v_sub_f32_e32 v120, v120, v22
	v_sub_f32_e32 v121, v121, v22
	v_mul_f32_e32 v106, 0x3fb8aa3b, v106
	v_mul_f32_e32 v107, 0x3fb8aa3b, v107
	v_mul_f32_e32 v108, 0x3fb8aa3b, v108
	v_mul_f32_e32 v109, 0x3fb8aa3b, v109
	v_mul_f32_e32 v110, 0x3fb8aa3b, v110
	v_mul_f32_e32 v111, 0x3fb8aa3b, v111
	v_mul_f32_e32 v112, 0x3fb8aa3b, v112
	v_mul_f32_e32 v113, 0x3fb8aa3b, v113
	v_mul_f32_e32 v114, 0x3fb8aa3b, v114
	v_mul_f32_e32 v115, 0x3fb8aa3b, v115
	v_mul_f32_e32 v116, 0x3fb8aa3b, v116
	v_mul_f32_e32 v117, 0x3fb8aa3b, v117
	v_mul_f32_e32 v118, 0x3fb8aa3b, v118
	v_mul_f32_e32 v119, 0x3fb8aa3b, v119
	v_mul_f32_e32 v120, 0x3fb8aa3b, v120
	v_mul_f32_e32 v121, 0x3fb8aa3b, v121
	v_exp_f32_e32 v106, v106
	v_exp_f32_e32 v107, v107
	v_exp_f32_e32 v108, v108
	v_exp_f32_e32 v109, v109
	v_exp_f32_e32 v110, v110
	v_exp_f32_e32 v111, v111
	v_exp_f32_e32 v112, v112
	v_exp_f32_e32 v113, v113
	v_exp_f32_e32 v114, v114
	v_exp_f32_e32 v115, v115
	v_exp_f32_e32 v116, v116
	v_exp_f32_e32 v117, v117
	v_exp_f32_e32 v118, v118
	v_exp_f32_e32 v119, v119
	v_exp_f32_e32 v120, v120
	v_exp_f32_e32 v121, v121
	v_mul_f32_e32 v122, v2, v122
	v_mul_f32_e32 v123, v3, v123
	v_mul_f32_e32 v124, v4, v124
	v_mul_f32_e32 v125, v5, v125
	v_mul_f32_e32 v126, v6, v126
	v_mul_f32_e32 v127, v7, v127
	v_mul_f32_e32 v128, v8, v128
	v_mul_f32_e32 v129, v9, v129
	v_mul_f32_e32 v26, v10, v26
	v_mul_f32_e32 v27, v11, v27
	v_mul_f32_e32 v28, v12, v28
	v_mul_f32_e32 v29, v13, v29
	v_mul_f32_e32 v30, v14, v30
	v_mul_f32_e32 v31, v15, v31
	v_mul_f32_e32 v32, v16, v32
	v_mul_f32_e32 v33, v17, v33
	v_mul_f32_e32 v106, v122, v106
	v_mul_f32_e32 v107, v123, v107
	v_mul_f32_e32 v108, v124, v108
	v_mul_f32_e32 v109, v125, v109
	v_mul_f32_e32 v110, v126, v110
	v_mul_f32_e32 v111, v127, v111
	v_mul_f32_e32 v112, v128, v112
	v_mul_f32_e32 v113, v129, v113
	v_mul_f32_e32 v114, v26, v114
	v_mul_f32_e32 v115, v27, v115
	v_mul_f32_e32 v116, v28, v116
	v_mul_f32_e32 v117, v29, v117
	v_mul_f32_e32 v118, v30, v118
	v_mul_f32_e32 v119, v31, v119
	v_mul_f32_e32 v120, v32, v120
	v_mul_f32_e32 v121, v33, v121
	v_cmp_lt_i32_e32 vcc, 27, v21
	v_cmp_lt_i32_e64 s[28:29], 26, v21
	v_cmp_lt_i32_e64 s[6:7], 25, v21
	v_cndmask_b32_e32 v106, 0, v106, vcc
	v_cmp_lt_i32_e32 vcc, 24, v21
	v_cndmask_b32_e64 v107, 0, v107, s[28:29]
	v_cmp_lt_i32_e64 s[28:29], 19, v21
	v_cndmask_b32_e64 v108, 0, v108, s[6:7]
	v_cmp_lt_i32_e64 s[6:7], 18, v21
	v_cndmask_b32_e32 v109, 0, v109, vcc
	v_cmp_lt_i32_e32 vcc, 17, v21
	v_cndmask_b32_e64 v110, 0, v110, s[28:29]
	v_cmp_lt_i32_e64 s[28:29], 16, v21
	v_cndmask_b32_e64 v111, 0, v111, s[6:7]
	v_cmp_lt_i32_e64 s[6:7], 11, v21
	v_cndmask_b32_e32 v112, 0, v112, vcc
	v_cmp_lt_i32_e32 vcc, 10, v21
	v_cndmask_b32_e64 v113, 0, v113, s[28:29]
	v_cmp_lt_i32_e64 s[28:29], 9, v21
	v_cndmask_b32_e64 v114, 0, v114, s[6:7]
	v_cmp_lt_i32_e64 s[6:7], 8, v21
	v_cndmask_b32_e32 v115, 0, v115, vcc
	v_cmp_lt_i32_e32 vcc, 3, v21
	v_cndmask_b32_e64 v116, 0, v116, s[28:29]
	v_cmp_lt_i32_e64 s[28:29], 2, v21
	v_cndmask_b32_e64 v117, 0, v117, s[6:7]
	v_cmp_lt_i32_e64 s[6:7], 1, v21
	v_cndmask_b32_e32 v118, 0, v118, vcc
	v_cmp_lt_i32_e32 vcc, 0, v21
	v_cndmask_b32_e64 v119, 0, v119, s[28:29]
	v_cndmask_b32_e64 v120, 0, v120, s[6:7]
	v_cndmask_b32_e32 v121, 0, v121, vcc
	ds_write_b128 v24, v[106:109]
	ds_write_b128 v24, v[110:113] offset:32
	ds_write_b128 v24, v[114:117] offset:64
	ds_write_b128 v24, v[118:121] offset:96
